# P0(b) filter MLP rewritten on f32 matrix cores (v_mfma_f32_16x16x4_f32, 16 positions per wave, activations via wave-private LDS tile)
# speedup vs baseline: 1.0062x; 1.0036x over previous
.LBB0_32:
	s_or_b64 exec, exec, s[0:1]
	s_movk_i32 s0, 0x600
	v_cmp_gt_i32_e32 vcc, s0, v66
	s_waitcnt lgkmcnt(0)
	s_barrier
	s_and_saveexec_b64 s[8:9], vcc
	s_cbranch_execz .LBB0_39
	v_and_b32_e32 v71, 15, v64
	v_lshrrev_b32_e32 v72, 4, v64
	v_readfirstlane_b32 s24, v66
	v_lshlrev_b32_e32 v67, 8, v72
	v_lshl_add_u32 v67, v71, 2, v67
	v_lshlrev_b32_e32 v70, 4, v72
	ds_read_b128 v[20:23], v70 offset:41984
	ds_read_b128 v[24:27], v70 offset:42048
	ds_read_b128 v[28:31], v70 offset:42112
	ds_read_b128 v[32:35], v70 offset:42176
	v_mul_u32_u24_e32 v73, 0x110, v71
	v_mul_u32_u24_e32 v74, 0x1100, v200
	v_add_u32_e32 v74, 0xa800, v74
	v_add_u32_e32 v73, v73, v74
	v_lshl_add_u32 v68, v72, 2, v73
	v_lshl_add_u32 v69, v72, 4, v73
	s_lshl_b32 s25, s24, 4
	s_mov_b32 s30, 0x38800000
	s_mov_b32 s31, 0x39000000
	s_mov_b32 s0, 0x467ffc00
	s_mov_b32 s1, 0x45fff800
	s_cmp_lt_u32 s25, 0x4000
	s_cselect_b32 s30, s30, s31
	s_cselect_b32 s31, s0, s1
	s_cselect_b32 s26, 0, 0x4000
	s_sub_u32 s27, s25, s26
	v_add_u32_e32 v75, s27, v71
	v_cvt_f32_i32_e32 v75, v75
	v_mov_b32_e32 v76, s31
	v_div_scale_f32 v82, s[36:37], v76, v76, v75
	v_rcp_f32_e32 v83, v82
	v_div_scale_f32 v84, vcc, v75, v76, v75
	v_fma_f32 v85, -v82, v83, 1.0
	v_fmac_f32_e32 v83, v85, v83
	v_mul_f32_e32 v85, v84, v83
	v_fma_f32 v86, -v82, v85, v84
	v_fmac_f32_e32 v85, v86, v83
	v_fma_f32 v82, -v82, v85, v84
	v_div_fmas_f32 v82, v82, v83, v85
	v_div_fixup_f32 v77, v82, v76, v75
	v_cmp_eq_u32_e64 s[0:1], 0, v72
	v_add_u32_e32 v78, -1, v72
	v_and_b32_e32 v78, 15, v78
	v_cvt_f32_ubyte0_e32 v78, v78
	v_mov_b32_e32 v79, 0x38d1b717
	v_fmac_f32_e32 v79, 0x3f7fff90, v78
	v_mul_f32_e32 v79, v79, v75
	v_mul_f32_e32 v79, s30, v79
	v_cos_f32_e32 v80, v79
	v_sin_f32_e64 v81, -v79
	v_add_u32_e32 v78, 3, v72
	v_and_b32_e32 v78, 15, v78
	v_cvt_f32_ubyte0_e32 v78, v78
	v_mov_b32_e32 v79, 0x38d1b717
	v_fmac_f32_e32 v79, 0x3f7fff90, v78
	v_mul_f32_e32 v79, v79, v75
	v_mul_f32_e32 v79, s30, v79
	v_cos_f32_e32 v37, v79
	v_sin_f32_e64 v41, -v79
	v_add_u32_e32 v78, 7, v72
	v_and_b32_e32 v78, 15, v78
	v_cvt_f32_ubyte0_e32 v78, v78
	v_mov_b32_e32 v79, 0x38d1b717
	v_fmac_f32_e32 v79, 0x3f7fff90, v78
	v_mul_f32_e32 v79, v79, v75
	v_mul_f32_e32 v79, s30, v79
	v_cos_f32_e32 v38, v79
	v_sin_f32_e64 v42, -v79
	v_add_u32_e32 v78, 11, v72
	v_and_b32_e32 v78, 15, v78
	v_cvt_f32_ubyte0_e32 v78, v78
	v_mov_b32_e32 v79, 0x38d1b717
	v_fmac_f32_e32 v79, 0x3f7fff90, v78
	v_mul_f32_e32 v79, v79, v75
	v_mul_f32_e32 v79, s30, v79
	v_cos_f32_e32 v39, v79
	v_sin_f32_e64 v43, -v79
	s_nop 0
	v_cndmask_b32_e64 v36, v80, v77, s[0:1]
	v_cndmask_b32_e64 v40, v81, v80, s[0:1]
	v_cndmask_b32_e64 v44, 0, v81, s[0:1]
	s_waitcnt lgkmcnt(0)
	v_mul_f32_e32 v20, 0.15915494, v20
	v_mul_f32_e32 v21, 0.15915494, v21
	v_mul_f32_e32 v22, 0.15915494, v22
	v_mul_f32_e32 v23, 0.15915494, v23
	v_mul_f32_e32 v24, 0.15915494, v24
	v_mul_f32_e32 v25, 0.15915494, v25
	v_mul_f32_e32 v26, 0.15915494, v26
	v_mul_f32_e32 v27, 0.15915494, v27
	v_mul_f32_e32 v28, 0.15915494, v28
	v_mul_f32_e32 v29, 0.15915494, v29
	v_mul_f32_e32 v30, 0.15915494, v30
	v_mul_f32_e32 v31, 0.15915494, v31
	v_mul_f32_e32 v32, 0.15915494, v32
	v_mul_f32_e32 v33, 0.15915494, v33
	v_mul_f32_e32 v34, 0.15915494, v34
	v_mul_f32_e32 v35, 0.15915494, v35
	s_add_u32 s26, s56, 0x1e420000
	s_addc_u32 s27, s57, 0
	s_lshl_b32 s4, s24, 11
	s_add_u32 s26, s26, s4
	s_addc_u32 s27, s27, 0
	v_lshlrev_b32_e32 v92, 7, v71
	v_lshl_add_u32 v92, v72, 3, v92
	s_mov_b32 s30, 0x7fff
	s_mov_b32 s31, 0x7060302
	ds_read_b128 v[4:7], v70 offset:41216
	ds_read_b128 v[8:11], v70 offset:41280
	ds_read_b128 v[12:15], v70 offset:41344
	ds_read_b128 v[16:19], v70 offset:41408
	ds_read_b32 v45, v67 offset:0
	ds_read_b32 v46, v67 offset:64
	ds_read_b32 v47, v67 offset:128
	ds_read_b32 v48, v67 offset:192
	ds_read_b32 v50, v67 offset:1024
	ds_read_b32 v51, v67 offset:1088
	ds_read_b32 v52, v67 offset:1152
	ds_read_b32 v53, v67 offset:1216
	s_waitcnt lgkmcnt(4)
	v_mfma_f32_16x16x4_f32 v[4:7], v45, v36, v[4:7]
	ds_read_b32 v55, v67 offset:2048
	ds_read_b32 v56, v67 offset:2112
	ds_read_b32 v57, v67 offset:2176
	ds_read_b32 v58, v67 offset:2240
	v_mfma_f32_16x16x4_f32 v[8:11], v46, v36, v[8:11]
	v_mfma_f32_16x16x4_f32 v[12:15], v47, v36, v[12:15]
	v_mfma_f32_16x16x4_f32 v[16:19], v48, v36, v[16:19]
	s_waitcnt lgkmcnt(4)
	v_mfma_f32_16x16x4_f32 v[4:7], v50, v37, v[4:7]
	ds_read_b32 v45, v67 offset:3072
	ds_read_b32 v46, v67 offset:3136
	ds_read_b32 v47, v67 offset:3200
	ds_read_b32 v48, v67 offset:3264
	v_mfma_f32_16x16x4_f32 v[8:11], v51, v37, v[8:11]
	v_mfma_f32_16x16x4_f32 v[12:15], v52, v37, v[12:15]
	v_mfma_f32_16x16x4_f32 v[16:19], v53, v37, v[16:19]
	s_waitcnt lgkmcnt(4)
	v_mfma_f32_16x16x4_f32 v[4:7], v55, v38, v[4:7]
	ds_read_b32 v50, v67 offset:4096
	ds_read_b32 v51, v67 offset:4160
	ds_read_b32 v52, v67 offset:4224
	ds_read_b32 v53, v67 offset:4288
	v_mfma_f32_16x16x4_f32 v[8:11], v56, v38, v[8:11]
	v_mfma_f32_16x16x4_f32 v[12:15], v57, v38, v[12:15]
	v_mfma_f32_16x16x4_f32 v[16:19], v58, v38, v[16:19]
	s_waitcnt lgkmcnt(4)
	v_mfma_f32_16x16x4_f32 v[4:7], v45, v39, v[4:7]
	ds_read_b32 v55, v67 offset:5120
	ds_read_b32 v56, v67 offset:5184
	ds_read_b32 v57, v67 offset:5248
	ds_read_b32 v58, v67 offset:5312
	v_mfma_f32_16x16x4_f32 v[8:11], v46, v39, v[8:11]
	v_mfma_f32_16x16x4_f32 v[12:15], v47, v39, v[12:15]
	v_mfma_f32_16x16x4_f32 v[16:19], v48, v39, v[16:19]
	s_waitcnt lgkmcnt(4)
	v_mfma_f32_16x16x4_f32 v[4:7], v50, v40, v[4:7]
	ds_read_b32 v45, v67 offset:6144
	ds_read_b32 v46, v67 offset:6208
	ds_read_b32 v47, v67 offset:6272
	ds_read_b32 v48, v67 offset:6336
	v_mfma_f32_16x16x4_f32 v[8:11], v51, v40, v[8:11]
	v_mfma_f32_16x16x4_f32 v[12:15], v52, v40, v[12:15]
	v_mfma_f32_16x16x4_f32 v[16:19], v53, v40, v[16:19]
	s_waitcnt lgkmcnt(4)
	v_mfma_f32_16x16x4_f32 v[4:7], v55, v41, v[4:7]
	ds_read_b32 v50, v67 offset:7168
	ds_read_b32 v51, v67 offset:7232
	ds_read_b32 v52, v67 offset:7296
	ds_read_b32 v53, v67 offset:7360
	v_mfma_f32_16x16x4_f32 v[8:11], v56, v41, v[8:11]
	v_mfma_f32_16x16x4_f32 v[12:15], v57, v41, v[12:15]
	v_mfma_f32_16x16x4_f32 v[16:19], v58, v41, v[16:19]
	s_waitcnt lgkmcnt(4)
	v_mfma_f32_16x16x4_f32 v[4:7], v45, v42, v[4:7]
	ds_read_b32 v55, v67 offset:8192
	ds_read_b32 v56, v67 offset:8256
	ds_read_b32 v57, v67 offset:8320
	ds_read_b32 v58, v67 offset:8384
	v_mfma_f32_16x16x4_f32 v[8:11], v46, v42, v[8:11]
	v_mfma_f32_16x16x4_f32 v[12:15], v47, v42, v[12:15]
	v_mfma_f32_16x16x4_f32 v[16:19], v48, v42, v[16:19]
	s_waitcnt lgkmcnt(4)
	v_mfma_f32_16x16x4_f32 v[4:7], v50, v43, v[4:7]
	v_mfma_f32_16x16x4_f32 v[8:11], v51, v43, v[8:11]
	v_mfma_f32_16x16x4_f32 v[12:15], v52, v43, v[12:15]
	v_mfma_f32_16x16x4_f32 v[16:19], v53, v43, v[16:19]
	s_waitcnt lgkmcnt(0)
	v_mfma_f32_16x16x4_f32 v[4:7], v55, v44, v[4:7]
	v_mfma_f32_16x16x4_f32 v[8:11], v56, v44, v[8:11]
	v_mfma_f32_16x16x4_f32 v[12:15], v57, v44, v[12:15]
	v_mfma_f32_16x16x4_f32 v[16:19], v58, v44, v[16:19]
	s_nop 7
	s_nop 3
	v_mul_f32_e32 v4, v20, v4
	v_mul_f32_e32 v5, v21, v5
	v_mul_f32_e32 v6, v22, v6
	v_mul_f32_e32 v7, v23, v7
	v_mul_f32_e32 v8, v24, v8
	v_mul_f32_e32 v9, v25, v9
	v_mul_f32_e32 v10, v26, v10
	v_mul_f32_e32 v11, v27, v11
	v_mul_f32_e32 v12, v28, v12
	v_mul_f32_e32 v13, v29, v13
	v_mul_f32_e32 v14, v30, v14
	v_mul_f32_e32 v15, v31, v15
	v_mul_f32_e32 v16, v32, v16
	v_mul_f32_e32 v17, v33, v17
	v_mul_f32_e32 v18, v34, v18
	v_mul_f32_e32 v19, v35, v19
	v_sin_f32_e32 v4, v4
	v_sin_f32_e32 v5, v5
	v_sin_f32_e32 v6, v6
	v_sin_f32_e32 v7, v7
	v_sin_f32_e32 v8, v8
	v_sin_f32_e32 v9, v9
	v_sin_f32_e32 v10, v10
	v_sin_f32_e32 v11, v11
	v_sin_f32_e32 v12, v12
	v_sin_f32_e32 v13, v13
	v_sin_f32_e32 v14, v14
	v_sin_f32_e32 v15, v15
	v_sin_f32_e32 v16, v16
	v_sin_f32_e32 v17, v17
	v_sin_f32_e32 v18, v18
	v_sin_f32_e32 v19, v19
	s_nop 1
	ds_write_b128 v69, v[4:7] offset:0
	ds_write_b128 v69, v[8:11] offset:64
	ds_write_b128 v69, v[12:15] offset:128
	ds_write_b128 v69, v[16:19] offset:192
	s_waitcnt lgkmcnt(0)
	ds_read_b128 v[100:103], v70 offset:41472
	ds_read_b128 v[104:107], v70 offset:41536
	ds_read_b128 v[108:111], v70 offset:41600
	ds_read_b128 v[112:115], v70 offset:41664
	ds_read_b32 v49, v68 offset:0
	ds_read_b32 v45, v67 offset:8448
	ds_read_b32 v46, v67 offset:8512
	ds_read_b32 v47, v67 offset:8576
	ds_read_b32 v48, v67 offset:8640
	ds_read_b32 v54, v68 offset:16
	ds_read_b32 v50, v67 offset:9472
	ds_read_b32 v51, v67 offset:9536
	ds_read_b32 v52, v67 offset:9600
	ds_read_b32 v53, v67 offset:9664
	s_waitcnt lgkmcnt(5)
	v_mfma_f32_16x16x4_f32 v[100:103], v45, v49, v[100:103]
	ds_read_b32 v59, v68 offset:32
	ds_read_b32 v55, v67 offset:10496
	ds_read_b32 v56, v67 offset:10560
	ds_read_b32 v57, v67 offset:10624
	ds_read_b32 v58, v67 offset:10688
	v_mfma_f32_16x16x4_f32 v[104:107], v46, v49, v[104:107]
	v_mfma_f32_16x16x4_f32 v[108:111], v47, v49, v[108:111]
	v_mfma_f32_16x16x4_f32 v[112:115], v48, v49, v[112:115]
	s_waitcnt lgkmcnt(5)
	v_mfma_f32_16x16x4_f32 v[100:103], v50, v54, v[100:103]
	ds_read_b32 v49, v68 offset:48
	ds_read_b32 v45, v67 offset:11520
	ds_read_b32 v46, v67 offset:11584
	ds_read_b32 v47, v67 offset:11648
	ds_read_b32 v48, v67 offset:11712
	v_mfma_f32_16x16x4_f32 v[104:107], v51, v54, v[104:107]
	v_mfma_f32_16x16x4_f32 v[108:111], v52, v54, v[108:111]
	v_mfma_f32_16x16x4_f32 v[112:115], v53, v54, v[112:115]
	s_waitcnt lgkmcnt(5)
	v_mfma_f32_16x16x4_f32 v[100:103], v55, v59, v[100:103]
	ds_read_b32 v54, v68 offset:64
	ds_read_b32 v50, v67 offset:12544
	ds_read_b32 v51, v67 offset:12608
	ds_read_b32 v52, v67 offset:12672
	ds_read_b32 v53, v67 offset:12736
	v_mfma_f32_16x16x4_f32 v[104:107], v56, v59, v[104:107]
	v_mfma_f32_16x16x4_f32 v[108:111], v57, v59, v[108:111]
	v_mfma_f32_16x16x4_f32 v[112:115], v58, v59, v[112:115]
	s_waitcnt lgkmcnt(5)
	v_mfma_f32_16x16x4_f32 v[100:103], v45, v49, v[100:103]
	ds_read_b32 v59, v68 offset:80
	ds_read_b32 v55, v67 offset:13568
	ds_read_b32 v56, v67 offset:13632
	ds_read_b32 v57, v67 offset:13696
	ds_read_b32 v58, v67 offset:13760
	v_mfma_f32_16x16x4_f32 v[104:107], v46, v49, v[104:107]
	v_mfma_f32_16x16x4_f32 v[108:111], v47, v49, v[108:111]
	v_mfma_f32_16x16x4_f32 v[112:115], v48, v49, v[112:115]
	s_waitcnt lgkmcnt(5)
	v_mfma_f32_16x16x4_f32 v[100:103], v50, v54, v[100:103]
	ds_read_b32 v49, v68 offset:96
	ds_read_b32 v45, v67 offset:14592
	ds_read_b32 v46, v67 offset:14656
	ds_read_b32 v47, v67 offset:14720
	ds_read_b32 v48, v67 offset:14784
	v_mfma_f32_16x16x4_f32 v[104:107], v51, v54, v[104:107]
	v_mfma_f32_16x16x4_f32 v[108:111], v52, v54, v[108:111]
	v_mfma_f32_16x16x4_f32 v[112:115], v53, v54, v[112:115]
	s_waitcnt lgkmcnt(5)
	v_mfma_f32_16x16x4_f32 v[100:103], v55, v59, v[100:103]
	ds_read_b32 v54, v68 offset:112
	ds_read_b32 v50, v67 offset:15616
	ds_read_b32 v51, v67 offset:15680
	ds_read_b32 v52, v67 offset:15744
	ds_read_b32 v53, v67 offset:15808
	v_mfma_f32_16x16x4_f32 v[104:107], v56, v59, v[104:107]
	v_mfma_f32_16x16x4_f32 v[108:111], v57, v59, v[108:111]
	v_mfma_f32_16x16x4_f32 v[112:115], v58, v59, v[112:115]
	s_waitcnt lgkmcnt(5)
	v_mfma_f32_16x16x4_f32 v[100:103], v45, v49, v[100:103]
	ds_read_b32 v59, v68 offset:128
	ds_read_b32 v55, v67 offset:16640
	ds_read_b32 v56, v67 offset:16704
	ds_read_b32 v57, v67 offset:16768
	ds_read_b32 v58, v67 offset:16832
	v_mfma_f32_16x16x4_f32 v[104:107], v46, v49, v[104:107]
	v_mfma_f32_16x16x4_f32 v[108:111], v47, v49, v[108:111]
	v_mfma_f32_16x16x4_f32 v[112:115], v48, v49, v[112:115]
	s_waitcnt lgkmcnt(5)
	v_mfma_f32_16x16x4_f32 v[100:103], v50, v54, v[100:103]
	ds_read_b32 v49, v68 offset:144
	ds_read_b32 v45, v67 offset:17664
	ds_read_b32 v46, v67 offset:17728
	ds_read_b32 v47, v67 offset:17792
	ds_read_b32 v48, v67 offset:17856
	v_mfma_f32_16x16x4_f32 v[104:107], v51, v54, v[104:107]
	v_mfma_f32_16x16x4_f32 v[108:111], v52, v54, v[108:111]
	v_mfma_f32_16x16x4_f32 v[112:115], v53, v54, v[112:115]
	s_waitcnt lgkmcnt(5)
	v_mfma_f32_16x16x4_f32 v[100:103], v55, v59, v[100:103]
	ds_read_b32 v54, v68 offset:160
	ds_read_b32 v50, v67 offset:18688
	ds_read_b32 v51, v67 offset:18752
	ds_read_b32 v52, v67 offset:18816
	ds_read_b32 v53, v67 offset:18880
	v_mfma_f32_16x16x4_f32 v[104:107], v56, v59, v[104:107]
	v_mfma_f32_16x16x4_f32 v[108:111], v57, v59, v[108:111]
	v_mfma_f32_16x16x4_f32 v[112:115], v58, v59, v[112:115]
	s_waitcnt lgkmcnt(5)
	v_mfma_f32_16x16x4_f32 v[100:103], v45, v49, v[100:103]
	ds_read_b32 v59, v68 offset:176
	ds_read_b32 v55, v67 offset:19712
	ds_read_b32 v56, v67 offset:19776
	ds_read_b32 v57, v67 offset:19840
	ds_read_b32 v58, v67 offset:19904
	v_mfma_f32_16x16x4_f32 v[104:107], v46, v49, v[104:107]
	v_mfma_f32_16x16x4_f32 v[108:111], v47, v49, v[108:111]
	v_mfma_f32_16x16x4_f32 v[112:115], v48, v49, v[112:115]
	s_waitcnt lgkmcnt(5)
	v_mfma_f32_16x16x4_f32 v[100:103], v50, v54, v[100:103]
	ds_read_b32 v49, v68 offset:192
	ds_read_b32 v45, v67 offset:20736
	ds_read_b32 v46, v67 offset:20800
	ds_read_b32 v47, v67 offset:20864
	ds_read_b32 v48, v67 offset:20928
	v_mfma_f32_16x16x4_f32 v[104:107], v51, v54, v[104:107]
	v_mfma_f32_16x16x4_f32 v[108:111], v52, v54, v[108:111]
	v_mfma_f32_16x16x4_f32 v[112:115], v53, v54, v[112:115]
	s_waitcnt lgkmcnt(5)
	v_mfma_f32_16x16x4_f32 v[100:103], v55, v59, v[100:103]
	ds_read_b32 v54, v68 offset:208
	ds_read_b32 v50, v67 offset:21760
	ds_read_b32 v51, v67 offset:21824
	ds_read_b32 v52, v67 offset:21888
	ds_read_b32 v53, v67 offset:21952
	v_mfma_f32_16x16x4_f32 v[104:107], v56, v59, v[104:107]
	v_mfma_f32_16x16x4_f32 v[108:111], v57, v59, v[108:111]
	v_mfma_f32_16x16x4_f32 v[112:115], v58, v59, v[112:115]
	s_waitcnt lgkmcnt(5)
	v_mfma_f32_16x16x4_f32 v[100:103], v45, v49, v[100:103]
	ds_read_b32 v59, v68 offset:224
	ds_read_b32 v55, v67 offset:22784
	ds_read_b32 v56, v67 offset:22848
	ds_read_b32 v57, v67 offset:22912
	ds_read_b32 v58, v67 offset:22976
	v_mfma_f32_16x16x4_f32 v[104:107], v46, v49, v[104:107]
	v_mfma_f32_16x16x4_f32 v[108:111], v47, v49, v[108:111]
	v_mfma_f32_16x16x4_f32 v[112:115], v48, v49, v[112:115]
	s_waitcnt lgkmcnt(5)
	v_mfma_f32_16x16x4_f32 v[100:103], v50, v54, v[100:103]
	ds_read_b32 v49, v68 offset:240
	ds_read_b32 v45, v67 offset:23808
	ds_read_b32 v46, v67 offset:23872
	ds_read_b32 v47, v67 offset:23936
	ds_read_b32 v48, v67 offset:24000
	v_mfma_f32_16x16x4_f32 v[104:107], v51, v54, v[104:107]
	v_mfma_f32_16x16x4_f32 v[108:111], v52, v54, v[108:111]
	v_mfma_f32_16x16x4_f32 v[112:115], v53, v54, v[112:115]
	s_waitcnt lgkmcnt(5)
	v_mfma_f32_16x16x4_f32 v[100:103], v55, v59, v[100:103]
	v_mfma_f32_16x16x4_f32 v[104:107], v56, v59, v[104:107]
	v_mfma_f32_16x16x4_f32 v[108:111], v57, v59, v[108:111]
	v_mfma_f32_16x16x4_f32 v[112:115], v58, v59, v[112:115]
	s_waitcnt lgkmcnt(0)
	v_mfma_f32_16x16x4_f32 v[100:103], v45, v49, v[100:103]
	v_mfma_f32_16x16x4_f32 v[104:107], v46, v49, v[104:107]
	v_mfma_f32_16x16x4_f32 v[108:111], v47, v49, v[108:111]
	v_mfma_f32_16x16x4_f32 v[112:115], v48, v49, v[112:115]
	s_nop 7
	s_nop 3
	v_mul_f32_e32 v100, v20, v100
	v_mul_f32_e32 v101, v21, v101
	v_mul_f32_e32 v102, v22, v102
	v_mul_f32_e32 v103, v23, v103
	v_mul_f32_e32 v104, v24, v104
	v_mul_f32_e32 v105, v25, v105
	v_mul_f32_e32 v106, v26, v106
	v_mul_f32_e32 v107, v27, v107
	v_mul_f32_e32 v108, v28, v108
	v_mul_f32_e32 v109, v29, v109
	v_mul_f32_e32 v110, v30, v110
	v_mul_f32_e32 v111, v31, v111
	v_mul_f32_e32 v112, v32, v112
	v_mul_f32_e32 v113, v33, v113
	v_mul_f32_e32 v114, v34, v114
	v_mul_f32_e32 v115, v35, v115
	v_sin_f32_e32 v100, v100
	v_sin_f32_e32 v101, v101
	v_sin_f32_e32 v102, v102
	v_sin_f32_e32 v103, v103
	v_sin_f32_e32 v104, v104
	v_sin_f32_e32 v105, v105
	v_sin_f32_e32 v106, v106
	v_sin_f32_e32 v107, v107
	v_sin_f32_e32 v108, v108
	v_sin_f32_e32 v109, v109
	v_sin_f32_e32 v110, v110
	v_sin_f32_e32 v111, v111
	v_sin_f32_e32 v112, v112
	v_sin_f32_e32 v113, v113
	v_sin_f32_e32 v114, v114
	v_sin_f32_e32 v115, v115
	s_nop 1
	ds_write_b128 v69, v[100:103] offset:0
	ds_write_b128 v69, v[104:107] offset:64
	ds_write_b128 v69, v[108:111] offset:128
	ds_write_b128 v69, v[112:115] offset:192
	s_waitcnt lgkmcnt(0)
	ds_read_b128 v[4:7], v70 offset:41728
	ds_read_b128 v[8:11], v70 offset:41792
	ds_read_b128 v[12:15], v70 offset:41856
	ds_read_b128 v[16:19], v70 offset:41920
	ds_read_b32 v49, v68 offset:0
	ds_read_b32 v45, v67 offset:24832
	ds_read_b32 v46, v67 offset:24896
	ds_read_b32 v47, v67 offset:24960
	ds_read_b32 v48, v67 offset:25024
	ds_read_b32 v54, v68 offset:16
	ds_read_b32 v50, v67 offset:25856
	ds_read_b32 v51, v67 offset:25920
	ds_read_b32 v52, v67 offset:25984
	ds_read_b32 v53, v67 offset:26048
	s_waitcnt lgkmcnt(5)
	v_mfma_f32_16x16x4_f32 v[4:7], v45, v49, v[4:7]
	ds_read_b32 v59, v68 offset:32
	ds_read_b32 v55, v67 offset:26880
	ds_read_b32 v56, v67 offset:26944
	ds_read_b32 v57, v67 offset:27008
	ds_read_b32 v58, v67 offset:27072
	v_mfma_f32_16x16x4_f32 v[8:11], v46, v49, v[8:11]
	v_mfma_f32_16x16x4_f32 v[12:15], v47, v49, v[12:15]
	v_mfma_f32_16x16x4_f32 v[16:19], v48, v49, v[16:19]
	s_waitcnt lgkmcnt(5)
	v_mfma_f32_16x16x4_f32 v[4:7], v50, v54, v[4:7]
	ds_read_b32 v49, v68 offset:48
	ds_read_b32 v45, v67 offset:27904
	ds_read_b32 v46, v67 offset:27968
	ds_read_b32 v47, v67 offset:28032
	ds_read_b32 v48, v67 offset:28096
	v_mfma_f32_16x16x4_f32 v[8:11], v51, v54, v[8:11]
	v_mfma_f32_16x16x4_f32 v[12:15], v52, v54, v[12:15]
	v_mfma_f32_16x16x4_f32 v[16:19], v53, v54, v[16:19]
	s_waitcnt lgkmcnt(5)
	v_mfma_f32_16x16x4_f32 v[4:7], v55, v59, v[4:7]
	ds_read_b32 v54, v68 offset:64
	ds_read_b32 v50, v67 offset:28928
	ds_read_b32 v51, v67 offset:28992
	ds_read_b32 v52, v67 offset:29056
	ds_read_b32 v53, v67 offset:29120
	v_mfma_f32_16x16x4_f32 v[8:11], v56, v59, v[8:11]
	v_mfma_f32_16x16x4_f32 v[12:15], v57, v59, v[12:15]
	v_mfma_f32_16x16x4_f32 v[16:19], v58, v59, v[16:19]
	s_waitcnt lgkmcnt(5)
	v_mfma_f32_16x16x4_f32 v[4:7], v45, v49, v[4:7]
	ds_read_b32 v59, v68 offset:80
	ds_read_b32 v55, v67 offset:29952
	ds_read_b32 v56, v67 offset:30016
	ds_read_b32 v57, v67 offset:30080
	ds_read_b32 v58, v67 offset:30144
	v_mfma_f32_16x16x4_f32 v[8:11], v46, v49, v[8:11]
	v_mfma_f32_16x16x4_f32 v[12:15], v47, v49, v[12:15]
	v_mfma_f32_16x16x4_f32 v[16:19], v48, v49, v[16:19]
	s_waitcnt lgkmcnt(5)
	v_mfma_f32_16x16x4_f32 v[4:7], v50, v54, v[4:7]
	ds_read_b32 v49, v68 offset:96
	ds_read_b32 v45, v67 offset:30976
	ds_read_b32 v46, v67 offset:31040
	ds_read_b32 v47, v67 offset:31104
	ds_read_b32 v48, v67 offset:31168
	v_mfma_f32_16x16x4_f32 v[8:11], v51, v54, v[8:11]
	v_mfma_f32_16x16x4_f32 v[12:15], v52, v54, v[12:15]
	v_mfma_f32_16x16x4_f32 v[16:19], v53, v54, v[16:19]
	s_waitcnt lgkmcnt(5)
	v_mfma_f32_16x16x4_f32 v[4:7], v55, v59, v[4:7]
	ds_read_b32 v54, v68 offset:112
	ds_read_b32 v50, v67 offset:32000
	ds_read_b32 v51, v67 offset:32064
	ds_read_b32 v52, v67 offset:32128
	ds_read_b32 v53, v67 offset:32192
	v_mfma_f32_16x16x4_f32 v[8:11], v56, v59, v[8:11]
	v_mfma_f32_16x16x4_f32 v[12:15], v57, v59, v[12:15]
	v_mfma_f32_16x16x4_f32 v[16:19], v58, v59, v[16:19]
	s_waitcnt lgkmcnt(5)
	v_mfma_f32_16x16x4_f32 v[4:7], v45, v49, v[4:7]
	ds_read_b32 v59, v68 offset:128
	ds_read_b32 v55, v67 offset:33024
	ds_read_b32 v56, v67 offset:33088
	ds_read_b32 v57, v67 offset:33152
	ds_read_b32 v58, v67 offset:33216
	v_mfma_f32_16x16x4_f32 v[8:11], v46, v49, v[8:11]
	v_mfma_f32_16x16x4_f32 v[12:15], v47, v49, v[12:15]
	v_mfma_f32_16x16x4_f32 v[16:19], v48, v49, v[16:19]
	s_waitcnt lgkmcnt(5)
	v_mfma_f32_16x16x4_f32 v[4:7], v50, v54, v[4:7]
	ds_read_b32 v49, v68 offset:144
	ds_read_b32 v45, v67 offset:34048
	ds_read_b32 v46, v67 offset:34112
	ds_read_b32 v47, v67 offset:34176
	ds_read_b32 v48, v67 offset:34240
	v_mfma_f32_16x16x4_f32 v[8:11], v51, v54, v[8:11]
	v_mfma_f32_16x16x4_f32 v[12:15], v52, v54, v[12:15]
	v_mfma_f32_16x16x4_f32 v[16:19], v53, v54, v[16:19]
	s_waitcnt lgkmcnt(5)
	v_mfma_f32_16x16x4_f32 v[4:7], v55, v59, v[4:7]
	ds_read_b32 v54, v68 offset:160
	ds_read_b32 v50, v67 offset:35072
	ds_read_b32 v51, v67 offset:35136
	ds_read_b32 v52, v67 offset:35200
	ds_read_b32 v53, v67 offset:35264
	v_mfma_f32_16x16x4_f32 v[8:11], v56, v59, v[8:11]
	v_mfma_f32_16x16x4_f32 v[12:15], v57, v59, v[12:15]
	v_mfma_f32_16x16x4_f32 v[16:19], v58, v59, v[16:19]
	s_waitcnt lgkmcnt(5)
	v_mfma_f32_16x16x4_f32 v[4:7], v45, v49, v[4:7]
	ds_read_b32 v59, v68 offset:176
	ds_read_b32 v55, v67 offset:36096
	ds_read_b32 v56, v67 offset:36160
	ds_read_b32 v57, v67 offset:36224
	ds_read_b32 v58, v67 offset:36288
	v_mfma_f32_16x16x4_f32 v[8:11], v46, v49, v[8:11]
	v_mfma_f32_16x16x4_f32 v[12:15], v47, v49, v[12:15]
	v_mfma_f32_16x16x4_f32 v[16:19], v48, v49, v[16:19]
	s_waitcnt lgkmcnt(5)
	v_mfma_f32_16x16x4_f32 v[4:7], v50, v54, v[4:7]
	ds_read_b32 v49, v68 offset:192
	ds_read_b32 v45, v67 offset:37120
	ds_read_b32 v46, v67 offset:37184
	ds_read_b32 v47, v67 offset:37248
	ds_read_b32 v48, v67 offset:37312
	v_mfma_f32_16x16x4_f32 v[8:11], v51, v54, v[8:11]
	v_mfma_f32_16x16x4_f32 v[12:15], v52, v54, v[12:15]
	v_mfma_f32_16x16x4_f32 v[16:19], v53, v54, v[16:19]
	s_waitcnt lgkmcnt(5)
	v_mfma_f32_16x16x4_f32 v[4:7], v55, v59, v[4:7]
	ds_read_b32 v54, v68 offset:208
	ds_read_b32 v50, v67 offset:38144
	ds_read_b32 v51, v67 offset:38208
	ds_read_b32 v52, v67 offset:38272
	ds_read_b32 v53, v67 offset:38336
	v_mfma_f32_16x16x4_f32 v[8:11], v56, v59, v[8:11]
	v_mfma_f32_16x16x4_f32 v[12:15], v57, v59, v[12:15]
	v_mfma_f32_16x16x4_f32 v[16:19], v58, v59, v[16:19]
	s_waitcnt lgkmcnt(5)
	v_mfma_f32_16x16x4_f32 v[4:7], v45, v49, v[4:7]
	ds_read_b32 v59, v68 offset:224
	ds_read_b32 v55, v67 offset:39168
	ds_read_b32 v56, v67 offset:39232
	ds_read_b32 v57, v67 offset:39296
	ds_read_b32 v58, v67 offset:39360
	v_mfma_f32_16x16x4_f32 v[8:11], v46, v49, v[8:11]
	v_mfma_f32_16x16x4_f32 v[12:15], v47, v49, v[12:15]
	v_mfma_f32_16x16x4_f32 v[16:19], v48, v49, v[16:19]
	s_waitcnt lgkmcnt(5)
	v_mfma_f32_16x16x4_f32 v[4:7], v50, v54, v[4:7]
	ds_read_b32 v49, v68 offset:240
	ds_read_b32 v45, v67 offset:40192
	ds_read_b32 v46, v67 offset:40256
	ds_read_b32 v47, v67 offset:40320
	ds_read_b32 v48, v67 offset:40384
	v_mfma_f32_16x16x4_f32 v[8:11], v51, v54, v[8:11]
	v_mfma_f32_16x16x4_f32 v[12:15], v52, v54, v[12:15]
	v_mfma_f32_16x16x4_f32 v[16:19], v53, v54, v[16:19]
	s_waitcnt lgkmcnt(5)
	v_mfma_f32_16x16x4_f32 v[4:7], v55, v59, v[4:7]
	v_mfma_f32_16x16x4_f32 v[8:11], v56, v59, v[8:11]
	v_mfma_f32_16x16x4_f32 v[12:15], v57, v59, v[12:15]
	v_mfma_f32_16x16x4_f32 v[16:19], v58, v59, v[16:19]
	s_waitcnt lgkmcnt(0)
	v_mfma_f32_16x16x4_f32 v[4:7], v45, v49, v[4:7]
	v_mfma_f32_16x16x4_f32 v[8:11], v46, v49, v[8:11]
	v_mfma_f32_16x16x4_f32 v[12:15], v47, v49, v[12:15]
	v_mfma_f32_16x16x4_f32 v[16:19], v48, v49, v[16:19]
	s_nop 7
	s_nop 3
	v_mul_f32_e32 v4, v20, v4
	v_mul_f32_e32 v5, v21, v5
	v_mul_f32_e32 v6, v22, v6
	v_mul_f32_e32 v7, v23, v7
	v_mul_f32_e32 v8, v24, v8
	v_mul_f32_e32 v9, v25, v9
	v_mul_f32_e32 v10, v26, v10
	v_mul_f32_e32 v11, v27, v11
	v_mul_f32_e32 v12, v28, v12
	v_mul_f32_e32 v13, v29, v13
	v_mul_f32_e32 v14, v30, v14
	v_mul_f32_e32 v15, v31, v15
	v_mul_f32_e32 v16, v32, v16
	v_mul_f32_e32 v17, v33, v17
	v_mul_f32_e32 v18, v34, v18
	v_mul_f32_e32 v19, v35, v19
	v_sin_f32_e32 v4, v4
	v_sin_f32_e32 v5, v5
	v_sin_f32_e32 v6, v6
	v_sin_f32_e32 v7, v7
	v_sin_f32_e32 v8, v8
	v_sin_f32_e32 v9, v9
	v_sin_f32_e32 v10, v10
	v_sin_f32_e32 v11, v11
	v_sin_f32_e32 v12, v12
	v_sin_f32_e32 v13, v13
	v_sin_f32_e32 v14, v14
	v_sin_f32_e32 v15, v15
	v_sin_f32_e32 v16, v16
	v_sin_f32_e32 v17, v17
	v_sin_f32_e32 v18, v18
	v_sin_f32_e32 v19, v19
	s_nop 1
	v_bfe_u32 v76, v4, 16, 1
	v_bfe_u32 v77, v5, 16, 1
	v_bfe_u32 v78, v6, 16, 1
	v_bfe_u32 v79, v7, 16, 1
	v_add3_u32 v4, v4, v76, s30
	v_add3_u32 v5, v5, v77, s30
	v_add3_u32 v6, v6, v78, s30
	v_add3_u32 v7, v7, v79, s30
	v_perm_b32 v4, v5, v4, s31
	v_perm_b32 v5, v7, v6, s31
	global_store_dwordx2 v92, v[4:5], s[26:27] offset:0
	v_bfe_u32 v76, v8, 16, 1
	v_bfe_u32 v77, v9, 16, 1
	v_bfe_u32 v78, v10, 16, 1
	v_bfe_u32 v79, v11, 16, 1
	v_add3_u32 v8, v8, v76, s30
	v_add3_u32 v9, v9, v77, s30
	v_add3_u32 v10, v10, v78, s30
	v_add3_u32 v11, v11, v79, s30
	v_perm_b32 v8, v9, v8, s31
	v_perm_b32 v9, v11, v10, s31
	global_store_dwordx2 v92, v[8:9], s[26:27] offset:32
	v_bfe_u32 v76, v12, 16, 1
	v_bfe_u32 v77, v13, 16, 1
	v_bfe_u32 v78, v14, 16, 1
	v_bfe_u32 v79, v15, 16, 1
	v_add3_u32 v12, v12, v76, s30
	v_add3_u32 v13, v13, v77, s30
	v_add3_u32 v14, v14, v78, s30
	v_add3_u32 v15, v15, v79, s30
	v_perm_b32 v12, v13, v12, s31
	v_perm_b32 v13, v15, v14, s31
	global_store_dwordx2 v92, v[12:13], s[26:27] offset:64
	v_bfe_u32 v76, v16, 16, 1
	v_bfe_u32 v77, v17, 16, 1
	v_bfe_u32 v78, v18, 16, 1
	v_bfe_u32 v79, v19, 16, 1
	v_add3_u32 v16, v16, v76, s30
	v_add3_u32 v17, v17, v77, s30
	v_add3_u32 v18, v18, v78, s30
	v_add3_u32 v19, v19, v79, s30
	v_perm_b32 v16, v17, v16, s31
	v_perm_b32 v17, v19, v18, s31
	global_store_dwordx2 v92, v[16:17], s[26:27] offset:96
